# mix phase previous-row load: all 8 loads in flight (global loads, counted vmcnt) instead of 5 loads, full wait, 3 loads (from v37)
# speedup vs baseline: 1.0035x; 1.0004x over previous
; DI void norm_row(const float* xrow, const float* g, int lane, f32x4 (&v)[8]) { load_row(xrow, lane, v); finish_row(g, lane, v); }
; DI void norm_row(const float* xrow, const LAS float* g, int lane, f32x4 (&v)[8]) { load_row(xrow, lane, v); finish_row(g, lane, v); }
; DI void mix_phase(unsigned char* lds, const Ctx& a, const Op& d) {
;     ...
;     for (int ch = gw; ch < MTOK / 8; ch += NGW) {
;         const int m0 = ch * 8;
;         f32x4 prev[8], cur[8];
;         if ((m0 % SEQ) == 0) {
; #pragma unroll
;             for (int j = 0; j < 8; ++j) prev[j] = (f32x4){0.f, 0.f, 0.f, 0.f};
;         } else norm_row(d.xin + (size_t)(m0 - 1) * DM, g, lane, prev);
.LBB0_553:
	v_mov_b32_e32 v96, v97
	v_lshlrev_b32_e32 v106, 3, v108
	v_and_b32_e32 v0, 0x1ff, v108
	v_mov_b32_e32 v98, v97
	v_mov_b32_e32 v99, v97
	v_mov_b64_e32 v[68:69], v[96:97]
	v_mov_b64_e32 v[56:57], v[96:97]
	v_mov_b64_e32 v[52:53], v[96:97]
	v_mov_b64_e32 v[48:49], v[96:97]
	v_mov_b64_e32 v[44:45], v[96:97]
	v_mov_b64_e32 v[40:41], v[96:97]
	v_mov_b64_e32 v[36:37], v[96:97]
	v_mov_b64_e32 v[32:33], v[96:97]
	v_cmp_ne_u32_e32 vcc, 0, v0
	v_ashrrev_i32_e32 v107, 31, v106
	v_add_u32_e32 v109, 0, v100
	v_mov_b64_e32 v[70:71], v[98:99]
	v_mov_b64_e32 v[58:59], v[98:99]
	v_mov_b64_e32 v[54:55], v[98:99]
	v_mov_b64_e32 v[50:51], v[98:99]
	v_mov_b64_e32 v[46:47], v[98:99]
	v_mov_b64_e32 v[42:43], v[98:99]
	v_mov_b64_e32 v[38:39], v[98:99]
	v_mov_b64_e32 v[34:35], v[98:99]
	s_and_saveexec_b64 s[8:9], vcc
	s_cbranch_execz .LBB0_555
; #define LAS __attribute__((address_space(3)))
; DI void load_row(const float* xrow, int lane, f32x4 (&v)[8]) {
; #pragma unroll
;     for (int j = 0; j < 8; ++j) v[j] = *(const f32x4*)(xrow + j * 256 + lane * 4);
; }
; DI void finish_row(const float* g, int lane, f32x4 (&v)[8]) {
;     float s = 0.f;
; #pragma unroll
;     for (int j = 0; j < 8; ++j) s += (v[j][0] * v[j][0] + v[j][1] * v[j][1]) + (v[j][2] * v[j][2] + v[j][3] * v[j][3]);
;     const float rstd = rsqrtf(wave_sum(s) * (1.0f / DM) + 1e-6f);
; #pragma unroll
;     for (int j = 0; j < 8; ++j) { const f32x4 gg = *(const f32x4*)(g + j * 256 + lane * 4); v[j] = v[j] * rstd * gg; }
; }
; DI void finish_row(const LAS float* g, int lane, f32x4 (&v)[8]) {
;     float s = 0.f;
; #pragma unroll
;     for (int j = 0; j < 8; ++j) s += (v[j][0] * v[j][0] + v[j][1] * v[j][1]) + (v[j][2] * v[j][2] + v[j][3] * v[j][3]);
;     const float rstd = rsqrtf(wave_sum(s) * (1.0f / DM) + 1e-6f);
; #pragma unroll
;     for (int j = 0; j < 8; ++j) { const f32x4 gg = *(const LAS f32x4*)(g + j * 256 + lane * 4); v[j] = v[j] * rstd * gg; }
; }
	v_lshlrev_b64 v[0:1], 13, v[106:107]
	v_lshl_add_u64 v[0:1], v[102:103], 0, v[0:1]
	s_movk_i32 s10, 0xe000
	v_add_co_u32_e32 v4, vcc, 0xffffe000, v0
	s_mov_b32 s11, -1
	s_nop 0
	v_addc_co_u32_e32 v5, vcc, -1, v1, vcc
	v_lshl_add_u64 v[2:3], v[0:1], 0, s[10:11]
	global_load_dwordx4 v[28:31], v[4:5], off
	global_load_dwordx4 v[24:27], v[2:3], off offset:1024
	global_load_dwordx4 v[20:23], v[2:3], off offset:2048
	global_load_dwordx4 v[16:19], v[2:3], off offset:3072
	v_add_co_u32_e32 v2, vcc, 0xfffff000, v0
	s_movk_i32 s10, 0xf800
	s_nop 0
	v_addc_co_u32_e32 v3, vcc, -1, v1, vcc
	global_load_dwordx4 v[12:15], v[2:3], off
	v_add_co_u32_e32 v2, vcc, 0xfffff400, v0
	s_nop 0
	s_nop 0
	v_addc_co_u32_e32 v3, vcc, -1, v1, vcc
	global_load_dwordx4 v[8:11], v[2:3], off
	v_add_co_u32_e32 v2, vcc, s10, v0
	s_nop 0
	s_nop 0
	v_addc_co_u32_e32 v3, vcc, -1, v1, vcc
	v_add_co_u32_e32 v0, vcc, 0xfffffc00, v0
	global_load_dwordx4 v[4:7], v[2:3], off
	s_nop 0
	v_addc_co_u32_e32 v1, vcc, -1, v1, vcc
	global_load_dwordx4 v[0:3], v[0:1], off
	s_waitcnt vmcnt(3)
	v_mov_b32_e32 v34, v29
	v_mov_b32_e32 v35, v25
	v_mov_b32_e32 v32, v28
	v_mov_b32_e32 v33, v24
	v_pk_mul_f32 v[34:35], v[34:35], v[34:35]
	v_mov_b32_e32 v36, v31
	v_mov_b32_e32 v37, v27
	v_pk_fma_f32 v[32:33], v[32:33], v[32:33], v[34:35]
	v_mov_b32_e32 v34, v30
	v_mov_b32_e32 v35, v26
	v_pk_mul_f32 v[36:37], v[36:37], v[36:37]
	s_nop 0
	v_pk_fma_f32 v[34:35], v[34:35], v[34:35], v[36:37]
	v_pk_mul_f32 v[36:37], v[20:21], v[20:21]
	v_pk_add_f32 v[32:33], v[32:33], v[34:35]
	v_pk_mul_f32 v[34:35], v[22:23], v[22:23]
	v_pk_add_f32 v[32:33], v[32:33], v[32:33] op_sel:[0,1] op_sel_hi:[1,0]
	v_pk_mov_b32 v[38:39], v[36:37], v[34:35] op_sel:[1,0]
	v_mov_b32_e32 v37, v35
	v_pk_add_f32 v[34:35], v[38:39], v[36:37]
	v_mul_f32_e32 v36, v12, v12
	v_mul_f32_e32 v37, v13, v13
	v_pk_add_f32 v[34:35], v[34:35], v[34:35] op_sel:[0,1] op_sel_hi:[1,0]
	v_mov_b32_e32 v33, v36
	v_mov_b32_e32 v35, v37
	v_pk_add_f32 v[32:33], v[32:33], v[34:35]
	v_mul_f32_e32 v34, v17, v17
	v_mul_f32_e32 v36, v19, v19
	v_mul_f32_e32 v38, v14, v14
	v_mul_f32_e32 v39, v15, v15
	v_pk_fma_f32 v[34:35], v[16:17], v[16:17], v[34:35] op_sel_hi:[1,1,0]
	v_pk_fma_f32 v[36:37], v[18:19], v[18:19], v[36:37] op_sel_hi:[1,1,0]
	v_mov_b32_e32 v35, v38
	v_mov_b32_e32 v37, v39
	v_pk_add_f32 v[34:35], v[34:35], v[36:37]
	s_waitcnt vmcnt(0) lgkmcnt(0)
	v_pk_mul_f32 v[36:37], v[8:9], v[8:9]
	v_pk_add_f32 v[32:33], v[32:33], v[34:35]
	v_pk_mul_f32 v[34:35], v[10:11], v[10:11]
	v_pk_add_f32 v[32:33], v[32:33], v[32:33] op_sel:[0,1] op_sel_hi:[1,0]
	v_pk_mov_b32 v[38:39], v[36:37], v[34:35] op_sel:[1,0]
	v_mov_b32_e32 v37, v35
	v_pk_add_f32 v[34:35], v[38:39], v[36:37]
	v_mul_f32_e32 v36, v0, v0
	v_mul_f32_e32 v37, v1, v1
	v_pk_add_f32 v[34:35], v[34:35], v[34:35] op_sel:[0,1] op_sel_hi:[1,0]
	v_mov_b32_e32 v33, v36
	v_mov_b32_e32 v35, v37
	v_pk_add_f32 v[32:33], v[32:33], v[34:35]
	v_mul_f32_e32 v34, v5, v5
	v_mul_f32_e32 v36, v7, v7
	v_mul_f32_e32 v38, v2, v2
	v_mul_f32_e32 v39, v3, v3
	v_pk_fma_f32 v[34:35], v[4:5], v[4:5], v[34:35] op_sel_hi:[1,1,0]
	v_pk_fma_f32 v[36:37], v[6:7], v[6:7], v[36:37] op_sel_hi:[1,1,0]
	v_mov_b32_e32 v35, v38
	v_mov_b32_e32 v37, v39
	v_pk_add_f32 v[34:35], v[34:35], v[36:37]
	s_nop 0
	v_pk_add_f32 v[32:33], v[32:33], v[34:35]
	s_nop 0
	v_add_f32_e32 v32, v32, v33
	s_nop 1
	v_add_f32_dpp v32, v32, v32 quad_perm:[1,0,3,2] row_mask:0xf bank_mask:0xf bound_ctrl:1
	s_nop 1
	v_add_f32_dpp v32, v32, v32 quad_perm:[2,3,0,1] row_mask:0xf bank_mask:0xf bound_ctrl:1
	s_nop 1
	v_add_f32_dpp v32, v32, v32 row_half_mirror row_mask:0xf bank_mask:0xf bound_ctrl:1
	s_nop 1
	v_add_f32_dpp v32, v32, v32 row_mirror row_mask:0xf bank_mask:0xf bound_ctrl:1
	s_nop 0
	v_readlane_b32 s17, v32, 16
	v_readlane_b32 s18, v32, 48
	v_readlane_b32 s10, v32, 0
	v_readlane_b32 s11, v32, 32
	v_mov_b32_e32 v32, s17
	v_mov_b32_e32 v33, s18
	v_pk_add_f32 v[32:33], s[10:11], v[32:33]
	s_nop 0
	v_add_f32_e32 v32, v32, v33
	v_fmamk_f32 v32, v32, 0x3a000000, v182
	v_cmp_gt_f32_e32 vcc, s33, v32
	v_mul_f32_e32 v33, 0x4b800000, v32
	s_nop 0
	v_cndmask_b32_e32 v32, v32, v33, vcc
	v_rsq_f32_e32 v32, v32
	s_nop 0
	v_mul_f32_e32 v33, 0x45800000, v32
	v_cndmask_b32_e32 v60, v32, v33, vcc
	ds_read_b128 v[32:35], v109
	v_pk_mul_f32 v[28:29], v[28:29], v[60:61] op_sel_hi:[1,0]
	v_pk_mul_f32 v[30:31], v[30:31], v[60:61] op_sel_hi:[1,0]
	v_pk_mul_f32 v[24:25], v[24:25], v[60:61] op_sel_hi:[1,0]
	v_pk_mul_f32 v[26:27], v[26:27], v[60:61] op_sel_hi:[1,0]
	s_waitcnt lgkmcnt(0)
	v_pk_mul_f32 v[34:35], v[34:35], v[30:31]
	v_pk_mul_f32 v[32:33], v[32:33], v[28:29]
	ds_read_b128 v[28:31], v109 offset:1024
	v_pk_mul_f32 v[20:21], v[20:21], v[60:61] op_sel_hi:[1,0]
	v_pk_mul_f32 v[22:23], v[22:23], v[60:61] op_sel_hi:[1,0]
	v_pk_mul_f32 v[16:17], v[16:17], v[60:61] op_sel_hi:[1,0]
	v_pk_mul_f32 v[18:19], v[18:19], v[60:61] op_sel_hi:[1,0]
	s_waitcnt lgkmcnt(0)
	v_pk_mul_f32 v[38:39], v[30:31], v[26:27]
	v_pk_mul_f32 v[36:37], v[28:29], v[24:25]
	ds_read_b128 v[24:27], v109 offset:2048
	v_pk_mul_f32 v[12:13], v[12:13], v[60:61] op_sel_hi:[1,0]
	v_pk_mul_f32 v[14:15], v[14:15], v[60:61] op_sel_hi:[1,0]
	v_pk_mul_f32 v[8:9], v[8:9], v[60:61] op_sel_hi:[1,0]
	v_pk_mul_f32 v[10:11], v[10:11], v[60:61] op_sel_hi:[1,0]
	s_waitcnt lgkmcnt(0)
	v_pk_mul_f32 v[42:43], v[26:27], v[22:23]
	v_pk_mul_f32 v[40:41], v[24:25], v[20:21]
	ds_read_b128 v[20:23], v109 offset:3072
	v_pk_mul_f32 v[4:5], v[4:5], v[60:61] op_sel_hi:[1,0]
	v_pk_mul_f32 v[6:7], v[6:7], v[60:61] op_sel_hi:[1,0]
	v_pk_mul_f32 v[0:1], v[0:1], v[60:61] op_sel_hi:[1,0]
	v_pk_mul_f32 v[2:3], v[2:3], v[60:61] op_sel_hi:[1,0]
	s_waitcnt lgkmcnt(0)
	v_pk_mul_f32 v[46:47], v[22:23], v[18:19]
	v_pk_mul_f32 v[44:45], v[20:21], v[16:17]
	ds_read_b128 v[16:19], v109 offset:4096
	s_waitcnt lgkmcnt(0)
	v_pk_mul_f32 v[50:51], v[18:19], v[14:15]
	v_pk_mul_f32 v[48:49], v[16:17], v[12:13]
	ds_read_b128 v[12:15], v109 offset:5120
	s_waitcnt lgkmcnt(0)
	v_pk_mul_f32 v[54:55], v[14:15], v[10:11]
	v_pk_mul_f32 v[52:53], v[12:13], v[8:9]
	ds_read_b128 v[8:11], v109 offset:6144
	s_waitcnt lgkmcnt(0)
	v_pk_mul_f32 v[58:59], v[10:11], v[6:7]
	v_pk_mul_f32 v[56:57], v[8:9], v[4:5]
	ds_read_b128 v[4:7], v109 offset:7168
	s_waitcnt lgkmcnt(0)
	v_pk_mul_f32 v[70:71], v[6:7], v[2:3]
	v_pk_mul_f32 v[68:69], v[4:5], v[0:1]
